# weight convert (all 4 layers) rewritten by hand: pipelined loads + double-buffered LDS transpose, same (w*gain)*cs->bf16 order
# speedup vs baseline: 1.0003x; 1.0003x over previous
; DI void conv_tile(LAS unsigned char* lds, const ConvJob& J, int t) {
;     ...
;   const int nkt = J.K / 64, nt_ = t / nkt, kt = t % nkt;
;   const int nn = tid & 255, np = nt_ * 256 + nn;
;   int src; float cs = 1.f;
;   if (J.mode == 0) src = np;
;   else if (J.mode == 1) { const int r = np & 255; src = (np & ~255) + ((r >> 5) & 3) * 64 + (r >> 7) * 32 + perm32(r & 31); }
;   else if (J.mode == 2) { const int r = np & 255; src = (r >> 7) * FFN_H + (np >> 8) * 128 + ((r >> 5) & 3) * 32 + perm32(r & 31); }
;   else { src = (np & ~31) + perm32(np & 31); if (src < 512) cs = 0.08838834764831845f; if (src >= 3104) src = -1; }
; DI void convert_layer(const Params& P, LAS unsigned char* lds, int li) {
;   bf16_t* W = (bf16_t*)(P.ws + OFF_W0 + (size_t)(li & 1) * W_BYTES);
;   const int j = li >> 1;
;   ConvJob J[4];
;   if ((li & 1) == 0) {
;     J[0] = ConvJob{P.in[3] + (size_t)j * DM * 9216, W + W_IN, P.in[1] + li * DM, DM, 9216, 9216, 1};
;     J[1] = ConvJob{P.in[6] + (size_t)j * DM * DM, W + W_OUT, nullptr, DM, DM, DM, 0};
;   } else {
;     J[0] = ConvJob{P.in[7] + (size_t)j * DM * 3104, W + W_IN, P.in[1] + li * DM, DM, 3104, 3328, 3};
;     J[1] = ConvJob{P.in[13] + (size_t)j * DM * DM, W + W_OUT, nullptr, DM, DM, DM, 0};
;   }
;   J[2] = ConvJob{P.in[14] + (size_t)li * DM * 2 * FFN_H, W + W_GU, P.in[2] + li * DM, DM, 2 * FFN_H, 2 * FFN_H, 2};
;   J[3] = ConvJob{P.in[15] + (size_t)li * FFN_H * DM, W + W_DN, nullptr, FFN_H, DM, DM, 0};
;   int cnt[4], tot = 0;
; #pragma unroll
;   for (int q = 0; q < 4; ++q) { cnt[q] = (J[q].Ndst / 256) * (J[q].K / 64); tot += cnt[q]; }
;   for (int t = blockIdx.x; t < tot; t += gridDim.x) {
;     int tt = t;
;     if (tt < cnt[0]) { conv_tile(lds, J[0], tt); continue; } tt -= cnt[0];
;     if (tt < cnt[1]) { conv_tile(lds, J[1], tt); continue; } tt -= cnt[1];
;     if (tt < cnt[2]) { conv_tile(lds, J[2], tt); continue; } tt -= cnt[2];
;     conv_tile(lds, J[3], tt);
.LBB0_531:
	v_readlane_b32 s0, v255, 7
	v_readlane_b32 s1, v255, 8
	s_andn2_b64 vcc, exec, s[0:1]
	s_cbranch_vccnz .LBB0_620
	v_readlane_b32 s0, v255, 6
	s_nop 0
	s_add_i32 s20, s0, 1
	s_and_b32 s14, s20, 1
	s_lshr_b32 s21, s20, 1
	s_movk_i32 s15, 1168
	s_cmp_lg_u32 s14, 0
	s_cselect_b32 s15, 800, s15
	s_cmp_ge_u32 s60, s15
	s_cbranch_scc1 .Lcva_exit
	s_mul_i32 s0, s14, 0x2500000
	s_add_u32 s18, s6, s0
	s_addc_u32 s19, s7, 0
	s_add_u32 s18, s18, 0x1000000
	s_addc_u32 s19, s19, 0
	v_and_b32_e32 v34, 0xff, v220
	v_lshrrev_b32_e32 v35, 8, v220
	v_and_b32_e32 v64, 31, v220
	v_bfe_u32 v36, v64, 2, 2
	v_lshlrev_b32_e32 v36, 3, v36
	v_lshrrev_b32_e32 v37, 4, v64
	v_lshl_add_u32 v36, v37, 2, v36
	v_and_b32_e32 v37, 3, v64
	v_add_u32_e32 v64, v36, v37
	v_bfe_u32 v36, v34, 5, 2
	v_lshrrev_b32_e32 v39, 7, v34
	v_lshlrev_b32_e32 v37, 6, v36
	v_lshl_add_u32 v37, v39, 5, v37
	v_add_u32_e32 v37, v37, v64
	v_mul_u32_u24_e32 v38, 0xb00, v39
	v_lshl_add_u32 v38, v36, 5, v38
	v_add_u32_e32 v38, v38, v64
	v_and_b32_e32 v39, 0xe0, v34
	v_add_u32_e32 v39, v39, v64
	v_mov_b32_e32 v36, v34
	v_mul_u32_u24_e32 v40, 0x101, v35
	v_add_u32_e32 v40, v40, v34
	v_lshlrev_b32_e32 v40, 2, v40
	v_and_b32_e32 v44, 7, v220
	v_lshrrev_b32_e32 v64, 3, v220
	v_mul_u32_u24_e32 v41, 0x808, v44
	v_add_u32_e32 v41, v41, v64
	v_lshlrev_b32_e32 v41, 2, v41
	v_lshlrev_b32_e32 v42, 11, v64
	v_lshl_add_u32 v42, v44, 4, v42
	v_mul_u32_u24_e32 v43, 0x1600, v64
	v_lshl_add_u32 v43, v44, 4, v43
	v_lshlrev_b32_e32 v44, 5, v44
	s_mov_b32 s13, s60
	s_mov_b32 s34, 0
	s_mov_b32 s0, s13
	s_movk_i32 s1, 576
	s_cmp_lg_u32 s14, 0
	s_cselect_b32 s1, 208, s1
	s_cmp_lt_u32 s0, s1
	s_cbranch_scc1 .Lcva_j00
	s_sub_u32 s0, s0, s1
	s_cmp_lt_u32 s0, 64
	s_cbranch_scc1 .Lcva_j10
	s_sub_u32 s0, s0, 64
	s_cmpk_lt_u32 s0, 0x160
	s_cbranch_scc1 .Lcva_j20
	s_sub_u32 s0, s0, 0x160
	s_mul_i32 s1, s0, 1490
	s_lshr_b32 s1, s1, 16
	s_mul_i32 s100, s1, 44
	s_sub_u32 s0, s0, s100
	v_readlane_b32 s36, v254, 53
	v_readlane_b32 s37, v254, 54
	s_mul_i32 s100, s20, 0xb00000
	s_add_u32 s36, s36, s100
	s_addc_u32 s37, s37, 0
	s_lshl_b32 s100, s0, 18
	s_add_u32 s36, s36, s100
	s_addc_u32 s37, s37, 0
	s_movk_i32 s38, 0x1000
	s_lshl_b32 s39, s1, 8
	s_mov_b32 s101, 0
	s_add_u32 s48, s18, 0x1f00000
	s_addc_u32 s49, s19, 0
	s_mul_i32 s100, s1, 0x160000
	s_add_u32 s48, s48, s100
	s_addc_u32 s49, s49, 0
	s_lshl_b32 s100, s0, 7
	s_add_u32 s48, s48, s100
	s_addc_u32 s49, s49, 0
	s_mov_b32 s50, 0x58000
	s_mov_b32 s51, 0
	s_mov_b32 s16, 1.0
	s_mov_b32 s17, 1
	s_mov_b32 s100, 0
	s_branch .Lcva_pd0
.Lcva_j20:
	s_lshr_b32 s1, s0, 4
	s_and_b32 s0, s0, 15
	v_readlane_b32 s36, v254, 51
	v_readlane_b32 s37, v254, 52
	s_mul_i32 s100, s20, 0x1600000
	s_add_u32 s36, s36, s100
	s_addc_u32 s37, s37, 0
	s_mul_i32 s100, s0, 0x160000
	s_add_u32 s36, s36, s100
	s_addc_u32 s37, s37, 0
	s_movk_i32 s38, 0x5800
	s_lshl_b32 s39, s1, 7
	s_mov_b32 s101, 2
	s_add_u32 s48, s18, 0x1400000
	s_addc_u32 s49, s19, 0
	v_readlane_b32 s28, v253, 22
	v_readlane_b32 s29, v253, 23
	s_mov_b32 s16, 1.0
	s_mov_b32 s100, 0
	s_branch .Lcva_pg0
.Lcva_j10:
	s_lshr_b32 s1, s0, 4
	s_and_b32 s0, s0, 15
	s_cmp_lg_u32 s14, 0
	s_cbranch_scc1 .Lcva_j1b0
	v_readlane_b32 s36, v253, 30
	v_readlane_b32 s37, v253, 31
	s_branch .Lcva_j1c0
.Lcva_j1b0:
	v_readlane_b32 s36, v254, 49
	v_readlane_b32 s37, v254, 50
.Lcva_j1c0:
	s_lshl_b32 s100, s21, 22
	s_add_u32 s36, s36, s100
	s_addc_u32 s37, s37, 0
	s_lshl_b32 s100, s0, 18
	s_add_u32 s36, s36, s100
	s_addc_u32 s37, s37, 0
	s_movk_i32 s38, 0x1000
	s_lshl_b32 s39, s1, 8
	s_mov_b32 s101, 0
	s_add_u32 s48, s18, 0x1200000
	s_addc_u32 s49, s19, 0
	s_mov_b32 s51, 0
	s_mov_b32 s16, 1.0
	s_mov_b32 s100, 0
	s_branch .Lcva_pk0
.Lcva_j00:
	s_lshr_b32 s1, s0, 4
	s_and_b32 s0, s0, 15
	s_lshl_b32 s39, s1, 8
	s_mov_b32 s16, 1.0
	s_mov_b32 s100, 0
	s_cmp_lg_u32 s14, 0
	s_cbranch_scc1 .Lcva_j0b0
	v_readlane_b32 s36, v253, 24
	v_readlane_b32 s37, v253, 25
	s_mul_i32 s100, s21, 0x2400000
	s_add_u32 s36, s36, s100
	s_addc_u32 s37, s37, 0
	s_mul_i32 s100, s0, 0x240000
	s_add_u32 s36, s36, s100
	s_addc_u32 s37, s37, 0
	s_mov_b32 s38, 0x9000
	s_mov_b32 s101, 1
	s_mov_b32 s100, 0
	s_branch .Lcva_j0c0
.Lcva_j0b0:
	v_readlane_b32 s36, v253, 32
	v_readlane_b32 s37, v253, 33
	s_mul_i32 s100, s21, 0xc20000
	s_add_u32 s36, s36, s100
	s_addc_u32 s37, s37, 0
	s_mul_i32 s100, s0, 0xc2000
	s_add_u32 s36, s36, s100
	s_addc_u32 s37, s37, 0
	s_movk_i32 s38, 0x3080
	s_mov_b32 s101, 3
	s_mov_b32 s100, 0
	s_cmp_lt_u32 s1, 2
	s_cselect_b32 s16, 0x3db504f3, s16
	s_cmp_eq_u32 s1, 12
	s_cselect_b32 s100, 1, 0
.Lcva_j0c0:
	s_mov_b32 s48, s18
	s_mov_b32 s49, s19
	v_readlane_b32 s28, v253, 20
	v_readlane_b32 s29, v253, 21
.Lcva_pg0:
	s_lshl_b32 s51, s20, 12
	s_add_u32 s28, s28, s51
	s_addc_u32 s29, s29, 0
	s_lshl_b32 s51, s0, 8
	s_add_u32 s28, s28, s51
	s_addc_u32 s29, s29, 0
	s_mov_b32 s51, 1
.Lcva_pk0:
	s_lshl_b32 s17, s1, 19
	s_add_u32 s48, s48, s17
	s_addc_u32 s49, s49, 0
	s_lshl_b32 s17, s0, 7
	s_add_u32 s48, s48, s17
	s_addc_u32 s49, s49, 0
	s_mov_b32 s50, 0x20000
	s_mov_b32 s17, 0
.Lcva_pd0:
	s_cmp_eq_u32 s101, 0
	s_cbranch_scc1 .Lcva_m00
	s_cmp_eq_u32 s101, 1
	s_cbranch_scc1 .Lcva_m10
	s_cmp_eq_u32 s101, 2
	s_cbranch_scc1 .Lcva_m20
	v_add_u32_e32 v46, s39, v39
	s_branch .Lcva_md0
.Lcva_m20:
	v_add_u32_e32 v46, s39, v38
	s_branch .Lcva_md0
.Lcva_m10:
	v_add_u32_e32 v46, s39, v37
	s_branch .Lcva_md0
.Lcva_m00:
	v_add_u32_e32 v46, s39, v36
.Lcva_md0:
	v_mov_b32_e32 v64, v46
	s_cmp_eq_u32 s100, 0
	s_cbranch_scc1 .Lcva_nc0
	v_min_u32_e32 v64, 0xc1f, v64
; DI void conv_tile(LAS unsigned char* lds, const ConvJob& J, int t) {
;     ...
;   float v[32];
; #pragma unroll
;   for (int e = 0; e < 32; ++e) {
;     const int k = kt * 64 + (tid >> 8) + 2 * e;
;     v[e] = (src >= 0) ? J.src[(size_t)k * J.Nsrc + src] : 0.f;
;   }
;   if (J.gain) {
; #pragma unroll
;     for (int e = 0; e < 32; ++e) v[e] *= J.gain[kt * 64 + (tid >> 8) + 2 * e];
;   }
;   __syncthreads();
; #pragma unroll
;   for (int e = 0; e < 32; ++e) tile[((tid >> 8) + 2 * e) * 257 + nn] = v[e] * cs;
; DI void convert_layer(const Params& P, LAS unsigned char* lds, int li) {
;     ...
;   for (int t = blockIdx.x; t < tot; t += gridDim.x) {
;     int tt = t;
;     if (tt < cnt[0]) { conv_tile(lds, J[0], tt); continue; } tt -= cnt[0];
;     if (tt < cnt[1]) { conv_tile(lds, J[1], tt); continue; } tt -= cnt[1];
;     if (tt < cnt[2]) { conv_tile(lds, J[2], tt); continue; } tt -= cnt[2];
;     conv_tile(lds, J[3], tt);
.Lcva_nc0:
	v_mul_lo_u32 v45, v35, s38
	v_lshl_add_u32 v45, v64, 2, v45
	s_lshl_b32 s0, s38, 1
	global_load_dword v2, v45, s[36:37]
	s_add_u32 s36, s36, s0
	s_addc_u32 s37, s37, 0
	global_load_dword v3, v45, s[36:37]
	s_add_u32 s36, s36, s0
	s_addc_u32 s37, s37, 0
	global_load_dword v4, v45, s[36:37]
	s_add_u32 s36, s36, s0
	s_addc_u32 s37, s37, 0
	global_load_dword v5, v45, s[36:37]
	s_add_u32 s36, s36, s0
	s_addc_u32 s37, s37, 0
	global_load_dword v6, v45, s[36:37]
	s_add_u32 s36, s36, s0
	s_addc_u32 s37, s37, 0
	global_load_dword v7, v45, s[36:37]
	s_add_u32 s36, s36, s0
	s_addc_u32 s37, s37, 0
	global_load_dword v8, v45, s[36:37]
	s_add_u32 s36, s36, s0
	s_addc_u32 s37, s37, 0
	global_load_dword v9, v45, s[36:37]
	s_add_u32 s36, s36, s0
	s_addc_u32 s37, s37, 0
	global_load_dword v10, v45, s[36:37]
	s_add_u32 s36, s36, s0
	s_addc_u32 s37, s37, 0
	global_load_dword v11, v45, s[36:37]
	s_add_u32 s36, s36, s0
	s_addc_u32 s37, s37, 0
	global_load_dword v12, v45, s[36:37]
	s_add_u32 s36, s36, s0
	s_addc_u32 s37, s37, 0
	global_load_dword v13, v45, s[36:37]
	s_add_u32 s36, s36, s0
	s_addc_u32 s37, s37, 0
	global_load_dword v14, v45, s[36:37]
	s_add_u32 s36, s36, s0
	s_addc_u32 s37, s37, 0
	global_load_dword v15, v45, s[36:37]
	s_add_u32 s36, s36, s0
	s_addc_u32 s37, s37, 0
	global_load_dword v16, v45, s[36:37]
	s_add_u32 s36, s36, s0
	s_addc_u32 s37, s37, 0
	global_load_dword v17, v45, s[36:37]
	s_add_u32 s36, s36, s0
	s_addc_u32 s37, s37, 0
	global_load_dword v18, v45, s[36:37]
	s_add_u32 s36, s36, s0
	s_addc_u32 s37, s37, 0
	global_load_dword v19, v45, s[36:37]
	s_add_u32 s36, s36, s0
	s_addc_u32 s37, s37, 0
	global_load_dword v20, v45, s[36:37]
	s_add_u32 s36, s36, s0
	s_addc_u32 s37, s37, 0
	global_load_dword v21, v45, s[36:37]
	s_add_u32 s36, s36, s0
	s_addc_u32 s37, s37, 0
	global_load_dword v22, v45, s[36:37]
	s_add_u32 s36, s36, s0
	s_addc_u32 s37, s37, 0
	global_load_dword v23, v45, s[36:37]
	s_add_u32 s36, s36, s0
	s_addc_u32 s37, s37, 0
	global_load_dword v24, v45, s[36:37]
	s_add_u32 s36, s36, s0
	s_addc_u32 s37, s37, 0
	global_load_dword v25, v45, s[36:37]
	s_add_u32 s36, s36, s0
	s_addc_u32 s37, s37, 0
	global_load_dword v26, v45, s[36:37]
	s_add_u32 s36, s36, s0
	s_addc_u32 s37, s37, 0
	global_load_dword v27, v45, s[36:37]
	s_add_u32 s36, s36, s0
	s_addc_u32 s37, s37, 0
	global_load_dword v28, v45, s[36:37]
	s_add_u32 s36, s36, s0
	s_addc_u32 s37, s37, 0
	global_load_dword v29, v45, s[36:37]
	s_add_u32 s36, s36, s0
	s_addc_u32 s37, s37, 0
	global_load_dword v30, v45, s[36:37]
	s_add_u32 s36, s36, s0
	s_addc_u32 s37, s37, 0
	global_load_dword v31, v45, s[36:37]
	s_add_u32 s36, s36, s0
	s_addc_u32 s37, s37, 0
	global_load_dword v32, v45, s[36:37]
	s_add_u32 s36, s36, s0
	s_addc_u32 s37, s37, 0
	global_load_dword v33, v45, s[36:37]
	s_waitcnt vmcnt(0) lgkmcnt(0)
	s_barrier
.Lcva_loop:
	s_mov_b64 s[40:41], s[48:49]
	s_mov_b32 s42, s50
	s_mov_b32 s43, s51
	s_mov_b64 s[44:45], s[28:29]
	s_mov_b32 s46, s16
	v_mov_b32_e32 v47, v46
	s_mov_b32 s1, s100
	s_waitcnt vmcnt(4)
	s_cmp_eq_u32 s1, 0
	s_cbranch_scc1 .Lcva_nz
	v_cmp_gt_u32_e32 vcc, 0xc20, v47
	s_nop 1
	v_cndmask_b32_e32 v2, 0, v2, vcc
	v_cndmask_b32_e32 v3, 0, v3, vcc
	v_cndmask_b32_e32 v4, 0, v4, vcc
	v_cndmask_b32_e32 v5, 0, v5, vcc
	v_cndmask_b32_e32 v6, 0, v6, vcc
	v_cndmask_b32_e32 v7, 0, v7, vcc
	v_cndmask_b32_e32 v8, 0, v8, vcc
	v_cndmask_b32_e32 v9, 0, v9, vcc
	v_cndmask_b32_e32 v10, 0, v10, vcc
	v_cndmask_b32_e32 v11, 0, v11, vcc
	v_cndmask_b32_e32 v12, 0, v12, vcc
	v_cndmask_b32_e32 v13, 0, v13, vcc
	v_cndmask_b32_e32 v14, 0, v14, vcc
	v_cndmask_b32_e32 v15, 0, v15, vcc
	v_cndmask_b32_e32 v16, 0, v16, vcc
	v_cndmask_b32_e32 v17, 0, v17, vcc
	v_cndmask_b32_e32 v18, 0, v18, vcc
	v_cndmask_b32_e32 v19, 0, v19, vcc
	v_cndmask_b32_e32 v20, 0, v20, vcc
	v_cndmask_b32_e32 v21, 0, v21, vcc
	v_cndmask_b32_e32 v22, 0, v22, vcc
	v_cndmask_b32_e32 v23, 0, v23, vcc
	v_cndmask_b32_e32 v24, 0, v24, vcc
	v_cndmask_b32_e32 v25, 0, v25, vcc
	v_cndmask_b32_e32 v26, 0, v26, vcc
	v_cndmask_b32_e32 v27, 0, v27, vcc
	v_cndmask_b32_e32 v28, 0, v28, vcc
	v_cndmask_b32_e32 v29, 0, v29, vcc
	v_cndmask_b32_e32 v30, 0, v30, vcc
	v_cndmask_b32_e32 v31, 0, v31, vcc
	v_cndmask_b32_e32 v32, 0, v32, vcc
	v_cndmask_b32_e32 v33, 0, v33, vcc
.Lcva_nz:
	v_add_u32_e32 v64, s34, v40
	ds_write_b32 v64, v2 offset:0
	ds_write_b32 v64, v3 offset:2056
	ds_write_b32 v64, v4 offset:4112
	ds_write_b32 v64, v5 offset:6168
	ds_write_b32 v64, v6 offset:8224
	ds_write_b32 v64, v7 offset:10280
	ds_write_b32 v64, v8 offset:12336
	ds_write_b32 v64, v9 offset:14392
	ds_write_b32 v64, v10 offset:16448
	ds_write_b32 v64, v11 offset:18504
	ds_write_b32 v64, v12 offset:20560
	ds_write_b32 v64, v13 offset:22616
	ds_write_b32 v64, v14 offset:24672
	ds_write_b32 v64, v15 offset:26728
	ds_write_b32 v64, v16 offset:28784
	ds_write_b32 v64, v17 offset:30840
	ds_write_b32 v64, v18 offset:32896
	ds_write_b32 v64, v19 offset:34952
	ds_write_b32 v64, v20 offset:37008
	ds_write_b32 v64, v21 offset:39064
	ds_write_b32 v64, v22 offset:41120
	ds_write_b32 v64, v23 offset:43176
	ds_write_b32 v64, v24 offset:45232
	ds_write_b32 v64, v25 offset:47288
	ds_write_b32 v64, v26 offset:49344
	ds_write_b32 v64, v27 offset:51400
	ds_write_b32 v64, v28 offset:53456
	ds_write_b32 v64, v29 offset:55512
	ds_write_b32 v64, v30 offset:57568
	ds_write_b32 v64, v31 offset:59624
	ds_write_b32 v64, v32 offset:61680
	ds_write_b32 v64, v33 offset:63736
	s_cmp_eq_u32 s43, 0
	s_cbranch_scc1 .Lcva_ng
	global_load_dwordx4 v[48:51], v44, s[44:45]
	global_load_dwordx4 v[52:55], v44, s[44:45] offset:16
.Lcva_ng:
	s_add_u32 s13, s13, s10
	s_cmp_lt_u32 s13, s15
	s_cbranch_scc0 .Lcva_nopre
	s_mov_b32 s0, s13
	s_movk_i32 s1, 576
	s_cmp_lg_u32 s14, 0
	s_cselect_b32 s1, 208, s1
	s_cmp_lt_u32 s0, s1
	s_cbranch_scc1 .Lcva_j01
	s_sub_u32 s0, s0, s1
	s_cmp_lt_u32 s0, 64
	s_cbranch_scc1 .Lcva_j11
	s_sub_u32 s0, s0, 64
	s_cmpk_lt_u32 s0, 0x160
	s_cbranch_scc1 .Lcva_j21
	s_sub_u32 s0, s0, 0x160
	s_mul_i32 s1, s0, 1490
	s_lshr_b32 s1, s1, 16
	s_mul_i32 s100, s1, 44
	s_sub_u32 s0, s0, s100
	v_readlane_b32 s36, v254, 53
	v_readlane_b32 s37, v254, 54
	s_mul_i32 s100, s20, 0xb00000
	s_add_u32 s36, s36, s100
	s_addc_u32 s37, s37, 0
	s_lshl_b32 s100, s0, 18
	s_add_u32 s36, s36, s100
	s_addc_u32 s37, s37, 0
	s_movk_i32 s38, 0x1000
	s_lshl_b32 s39, s1, 8
	s_mov_b32 s101, 0
	s_add_u32 s48, s18, 0x1f00000
	s_addc_u32 s49, s19, 0
	s_mul_i32 s100, s1, 0x160000
	s_add_u32 s48, s48, s100
	s_addc_u32 s49, s49, 0
	s_lshl_b32 s100, s0, 7
	s_add_u32 s48, s48, s100
	s_addc_u32 s49, s49, 0
	s_mov_b32 s50, 0x58000
	s_mov_b32 s51, 0
	s_mov_b32 s16, 1.0
	s_mov_b32 s17, 1
	s_mov_b32 s100, 0
	s_branch .Lcva_pd1

; DI void conv_tile(LAS unsigned char* lds, const ConvJob& J, int t) {
;     ...
;   float v[32];
; #pragma unroll
;   for (int e = 0; e < 32; ++e) {
;     const int k = kt * 64 + (tid >> 8) + 2 * e;
;     v[e] = (src >= 0) ? J.src[(size_t)k * J.Nsrc + src] : 0.f;
;   }
.Lcva_nc1:
	v_mul_lo_u32 v45, v35, s38
	v_lshl_add_u32 v45, v64, 2, v45
	s_lshl_b32 s0, s38, 1
	global_load_dword v2, v45, s[36:37]
	s_add_u32 s36, s36, s0
	s_addc_u32 s37, s37, 0
	global_load_dword v3, v45, s[36:37]
	s_add_u32 s36, s36, s0
	s_addc_u32 s37, s37, 0
	global_load_dword v4, v45, s[36:37]
	s_add_u32 s36, s36, s0
	s_addc_u32 s37, s37, 0
	global_load_dword v5, v45, s[36:37]
	s_add_u32 s36, s36, s0
	s_addc_u32 s37, s37, 0
	global_load_dword v6, v45, s[36:37]
	s_add_u32 s36, s36, s0
	s_addc_u32 s37, s37, 0
	global_load_dword v7, v45, s[36:37]
	s_add_u32 s36, s36, s0
	s_addc_u32 s37, s37, 0
	global_load_dword v8, v45, s[36:37]
	s_add_u32 s36, s36, s0
	s_addc_u32 s37, s37, 0
	global_load_dword v9, v45, s[36:37]
	s_add_u32 s36, s36, s0
	s_addc_u32 s37, s37, 0
	global_load_dword v10, v45, s[36:37]
	s_add_u32 s36, s36, s0
	s_addc_u32 s37, s37, 0
	global_load_dword v11, v45, s[36:37]
	s_add_u32 s36, s36, s0
	s_addc_u32 s37, s37, 0
	global_load_dword v12, v45, s[36:37]
	s_add_u32 s36, s36, s0
	s_addc_u32 s37, s37, 0
	global_load_dword v13, v45, s[36:37]
	s_add_u32 s36, s36, s0
	s_addc_u32 s37, s37, 0
	global_load_dword v14, v45, s[36:37]
	s_add_u32 s36, s36, s0
	s_addc_u32 s37, s37, 0
	global_load_dword v15, v45, s[36:37]
	s_add_u32 s36, s36, s0
	s_addc_u32 s37, s37, 0
	global_load_dword v16, v45, s[36:37]
	s_add_u32 s36, s36, s0
	s_addc_u32 s37, s37, 0
	global_load_dword v17, v45, s[36:37]
	s_add_u32 s36, s36, s0
	s_addc_u32 s37, s37, 0
	global_load_dword v18, v45, s[36:37]
	s_add_u32 s36, s36, s0
	s_addc_u32 s37, s37, 0
	global_load_dword v19, v45, s[36:37]
	s_add_u32 s36, s36, s0
	s_addc_u32 s37, s37, 0
	global_load_dword v20, v45, s[36:37]
	s_add_u32 s36, s36, s0
	s_addc_u32 s37, s37, 0
	global_load_dword v21, v45, s[36:37]
	s_add_u32 s36, s36, s0
	s_addc_u32 s37, s37, 0
	global_load_dword v22, v45, s[36:37]
	s_add_u32 s36, s36, s0
	s_addc_u32 s37, s37, 0
	global_load_dword v23, v45, s[36:37]
	s_add_u32 s36, s36, s0
	s_addc_u32 s37, s37, 0
	global_load_dword v24, v45, s[36:37]
	s_add_u32 s36, s36, s0
	s_addc_u32 s37, s37, 0
	global_load_dword v25, v45, s[36:37]
	s_add_u32 s36, s36, s0
	s_addc_u32 s37, s37, 0
	global_load_dword v26, v45, s[36:37]
	s_add_u32 s36, s36, s0
	s_addc_u32 s37, s37, 0
	global_load_dword v27, v45, s[36:37]
	s_add_u32 s36, s36, s0
	s_addc_u32 s37, s37, 0
	global_load_dword v28, v45, s[36:37]
	s_add_u32 s36, s36, s0
	s_addc_u32 s37, s37, 0
	global_load_dword v29, v45, s[36:37]
	s_add_u32 s36, s36, s0
	s_addc_u32 s37, s37, 0
	global_load_dword v30, v45, s[36:37]
	s_add_u32 s36, s36, s0
	s_addc_u32 s37, s37, 0
	global_load_dword v31, v45, s[36:37]
	s_add_u32 s36, s36, s0
	s_addc_u32 s37, s37, 0
	global_load_dword v32, v45, s[36:37]
	s_add_u32 s36, s36, s0
	s_addc_u32 s37, s37, 0
	global_load_dword v33, v45, s[36:37]
	s_waitcnt vmcnt(32) lgkmcnt(0)
	s_branch .Lcva_sync

; DI unsigned cvt_pk(float lo, float hi) { unsigned r; asm("v_cvt_pk_bf16_f32 %0, %1, %2" : "=v"(r) : "v"(lo), "v"(hi)); return r; }
; DI void conv_tile(LAS unsigned char* lds, const ConvJob& J, int t) {
;     ...
;   if (J.gain) {
; #pragma unroll
;     for (int e = 0; e < 32; ++e) v[e] *= J.gain[kt * 64 + (tid >> 8) + 2 * e];
;   }
;     ...
; #pragma unroll
;   for (int p = 0; p < 4; ++p) {
;     const int n2 = (tid >> 3) + 64 * p, kc = tid & 7;
;     float f[8];
; #pragma unroll
;     for (int j = 0; j < 8; ++j) f[j] = tile[(kc * 8 + j) * 257 + n2];
;     u32x4 w; w.x = cvt_pk(f[0], f[1]); w.y = cvt_pk(f[2], f[3]); w.z = cvt_pk(f[4], f[5]); w.w = cvt_pk(f[6], f[7]);
;     *(u32x4*)(J.dst + (size_t)(nt_ * 256 + n2) * J.K + kt * 64 + kc * 8) = w;
;   }
.Lcva_sync:
	s_barrier
	v_add_u32_e32 v64, s34, v41
	s_cmp_eq_u32 s42, 0x20000
	s_cselect_b32 s0, 0, 1
	ds_read_b32 v56, v64 offset:0
	ds_read_b32 v57, v64 offset:1028
	ds_read_b32 v58, v64 offset:2056
	ds_read_b32 v59, v64 offset:3084
	ds_read_b32 v60, v64 offset:4112
	ds_read_b32 v61, v64 offset:5140
	ds_read_b32 v62, v64 offset:6168
	ds_read_b32 v63, v64 offset:7196
	s_waitcnt lgkmcnt(0)
	s_cmp_eq_u32 s43, 0
	s_cbranch_scc1 .Lcva_og0
	v_mul_f32_e32 v56, v56, v48
	v_mul_f32_e32 v57, v57, v49
	v_mul_f32_e32 v58, v58, v50
	v_mul_f32_e32 v59, v59, v51
	v_mul_f32_e32 v60, v60, v52
	v_mul_f32_e32 v61, v61, v53
	v_mul_f32_e32 v62, v62, v54
	v_mul_f32_e32 v63, v63, v55
.Lcva_og0:
	s_cmp_eq_u32 s46, 1.0
	s_cbranch_scc1 .Lcva_oc0
	v_mul_f32_e32 v56, s46, v56
	v_mul_f32_e32 v57, s46, v57
	v_mul_f32_e32 v58, s46, v58
	v_mul_f32_e32 v59, s46, v59
	v_mul_f32_e32 v60, s46, v60
	v_mul_f32_e32 v61, s46, v61
	v_mul_f32_e32 v62, s46, v62
	v_mul_f32_e32 v63, s46, v63
.Lcva_oc0:
	v_cvt_pk_bf16_f32 v56, v56, v57
	v_cvt_pk_bf16_f32 v57, v58, v59
	v_cvt_pk_bf16_f32 v58, v60, v61
	v_cvt_pk_bf16_f32 v59, v62, v63
	s_cmp_eq_u32 s0, 0
	s_cbranch_scc0 .Lcva_o50
	global_store_dwordx4 v42, v[56:59], s[40:41]
	s_branch .Lcva_od0
.Lcva_o50:
	global_store_dwordx4 v43, v[56:59], s[40:41]
.Lcva_od0:
	s_add_u32 s40, s40, s42
	s_addc_u32 s41, s41, 0
	ds_read_b32 v56, v64 offset:256
	ds_read_b32 v57, v64 offset:1284
	ds_read_b32 v58, v64 offset:2312
	ds_read_b32 v59, v64 offset:3340
	ds_read_b32 v60, v64 offset:4368
	ds_read_b32 v61, v64 offset:5396
	ds_read_b32 v62, v64 offset:6424
	ds_read_b32 v63, v64 offset:7452
	s_waitcnt lgkmcnt(0)
	s_cmp_eq_u32 s43, 0
	s_cbranch_scc1 .Lcva_og1
	v_mul_f32_e32 v56, v56, v48
	v_mul_f32_e32 v57, v57, v49
	v_mul_f32_e32 v58, v58, v50
	v_mul_f32_e32 v59, v59, v51
	v_mul_f32_e32 v60, v60, v52
	v_mul_f32_e32 v61, v61, v53
	v_mul_f32_e32 v62, v62, v54
	v_mul_f32_e32 v63, v63, v55

; DI unsigned cvt_pk(float lo, float hi) { unsigned r; asm("v_cvt_pk_bf16_f32 %0, %1, %2" : "=v"(r) : "v"(lo), "v"(hi)); return r; }
; DI void conv_tile(LAS unsigned char* lds, const ConvJob& J, int t) {
;     ...
; #pragma unroll
;   for (int p = 0; p < 4; ++p) {
;     const int n2 = (tid >> 3) + 64 * p, kc = tid & 7;
;     float f[8];
; #pragma unroll
;     for (int j = 0; j < 8; ++j) f[j] = tile[(kc * 8 + j) * 257 + n2];
;     u32x4 w; w.x = cvt_pk(f[0], f[1]); w.y = cvt_pk(f[2], f[3]); w.z = cvt_pk(f[4], f[5]); w.w = cvt_pk(f[6], f[7]);
;     *(u32x4*)(J.dst + (size_t)(nt_ * 256 + n2) * J.K + kt * 64 + kc * 8) = w;
.Lcva_od1:
	s_add_u32 s40, s40, s42
	s_addc_u32 s41, s41, 0
	ds_read_b32 v56, v64 offset:512
	ds_read_b32 v57, v64 offset:1540
	ds_read_b32 v58, v64 offset:2568
	ds_read_b32 v59, v64 offset:3596
	ds_read_b32 v60, v64 offset:4624
	ds_read_b32 v61, v64 offset:5652
	ds_read_b32 v62, v64 offset:6680
	ds_read_b32 v63, v64 offset:7708
	s_waitcnt lgkmcnt(0)
	s_cmp_eq_u32 s43, 0
	s_cbranch_scc1 .Lcva_og2
	v_mul_f32_e32 v56, v56, v48
	v_mul_f32_e32 v57, v57, v49
	v_mul_f32_e32 v58, v58, v50
	v_mul_f32_e32 v59, v59, v51
	v_mul_f32_e32 v60, v60, v52
	v_mul_f32_e32 v61, v61, v53
	v_mul_f32_e32 v62, v62, v54
	v_mul_f32_e32 v63, v63, v55

; DI unsigned cvt_pk(float lo, float hi) { unsigned r; asm("v_cvt_pk_bf16_f32 %0, %1, %2" : "=v"(r) : "v"(lo), "v"(hi)); return r; }
; DI void conv_tile(LAS unsigned char* lds, const ConvJob& J, int t) {
;     ...
; #pragma unroll
;   for (int p = 0; p < 4; ++p) {
;     const int n2 = (tid >> 3) + 64 * p, kc = tid & 7;
;     float f[8];
; #pragma unroll
;     for (int j = 0; j < 8; ++j) f[j] = tile[(kc * 8 + j) * 257 + n2];
;     u32x4 w; w.x = cvt_pk(f[0], f[1]); w.y = cvt_pk(f[2], f[3]); w.z = cvt_pk(f[4], f[5]); w.w = cvt_pk(f[6], f[7]);
;     *(u32x4*)(J.dst + (size_t)(nt_ * 256 + n2) * J.K + kt * 64 + kc * 8) = w;
.Lcva_od2:
	s_add_u32 s40, s40, s42
	s_addc_u32 s41, s41, 0
	ds_read_b32 v56, v64 offset:768
	ds_read_b32 v57, v64 offset:1796
	ds_read_b32 v58, v64 offset:2824
	ds_read_b32 v59, v64 offset:3852
	ds_read_b32 v60, v64 offset:4880
	ds_read_b32 v61, v64 offset:5908
	ds_read_b32 v62, v64 offset:6936
	ds_read_b32 v63, v64 offset:7964
	s_waitcnt lgkmcnt(0)
	s_cmp_eq_u32 s43, 0
	s_cbranch_scc1 .Lcva_og3
	v_mul_f32_e32 v56, v56, v48
	v_mul_f32_e32 v57, v57, v49
	v_mul_f32_e32 v58, v58, v50
	v_mul_f32_e32 v59, v59, v51
	v_mul_f32_e32 v60, v60, v52
	v_mul_f32_e32 v61, v61, v53
	v_mul_f32_e32 v62, v62, v54
	v_mul_f32_e32 v63, v63, v55

; DI void convert_layer(const Params& P, LAS unsigned char* lds, int li) {
;     ...
;   for (int t = blockIdx.x; t < tot; t += gridDim.x) {
;     int tt = t;
;     if (tt < cnt[0]) { conv_tile(lds, J[0], tt); continue; } tt -= cnt[0];
;     if (tt < cnt[1]) { conv_tile(lds, J[1], tt); continue; } tt -= cnt[1];
;     if (tt < cnt[2]) { conv_tile(lds, J[2], tt); continue; } tt -= cnt[2];
;     conv_tile(lds, J[3], tt);
;   }
;   __syncthreads();
.Lcva_od3:
	s_xor_b32 s34, s34, 0x10100
	s_cmp_lt_u32 s13, s15
	s_cbranch_scc1 .Lcva_loop
.Lcva_exit:
.LBB0_619:
	s_mov_b32 s85, 0x34000
	s_mov_b64 s[72:73], -1
	s_mov_b64 s[58:59], s[2:3]
	s_waitcnt vmcnt(0) lgkmcnt(0)
	s_barrier

; #define LAS __attribute__((address_space(3)))
; DI void convert_layer(const Params& P, LAS unsigned char* lds, int li) {
;   bf16_t* W = (bf16_t*)(P.ws + OFF_W0 + (size_t)(li & 1) * W_BYTES);
;   const int j = li >> 1;
;   ConvJob J[4];
;   if ((li & 1) == 0) {
;     J[0] = ConvJob{P.in[3] + (size_t)j * DM * 9216, W + W_IN, P.in[1] + li * DM, DM, 9216, 9216, 1};
;     J[1] = ConvJob{P.in[6] + (size_t)j * DM * DM, W + W_OUT, nullptr, DM, DM, DM, 0};
;   } else {
;     J[0] = ConvJob{P.in[7] + (size_t)j * DM * 3104, W + W_IN, P.in[1] + li * DM, DM, 3104, 3328, 3};
;     J[1] = ConvJob{P.in[13] + (size_t)j * DM * DM, W + W_OUT, nullptr, DM, DM, DM, 0};
;   }
;   J[2] = ConvJob{P.in[14] + (size_t)li * DM * 2 * FFN_H, W + W_GU, P.in[2] + li * DM, DM, 2 * FFN_H, 2 * FFN_H, 2};
;   J[3] = ConvJob{P.in[15] + (size_t)li * FFN_H * DM, W + W_DN, nullptr, FFN_H, DM, DM, 0};
;   int cnt[4], tot = 0;
; #pragma unroll
;   for (int q = 0; q < 4; ++q) { cnt[q] = (J[q].Ndst / 256) * (J[q].K / 64); tot += cnt[q]; }
;   for (int t = blockIdx.x; t < tot; t += gridDim.x) {
;     int tt = t;
;     if (tt < cnt[0]) { conv_tile(lds, J[0], tt); continue; } tt -= cnt[0];
;     if (tt < cnt[1]) { conv_tile(lds, J[1], tt); continue; } tt -= cnt[1];
;     if (tt < cnt[2]) { conv_tile(lds, J[2], tt); continue; } tt -= cnt[2];
;     conv_tile(lds, J[3], tt);
; DI void prep_phase(const Params& P, LAS unsigned char* lds) {
;     ...
;   convert_layer(P, lds, 0);
.LBB0_633:
	s_or_b64 exec, exec, s[14:15]
	v_readlane_b32 s0, v254, 22
	v_readlane_b32 s1, v254, 23
	s_andn2_b64 vcc, exec, s[0:1]
	s_cbranch_vccnz .LBB0_716
	s_mov_b32 s20, 0
	s_and_b32 s14, s20, 1
	s_lshr_b32 s21, s20, 1
	s_movk_i32 s15, 1168
	s_cmp_lg_u32 s14, 0
	s_cselect_b32 s15, 800, s15
	s_cmp_ge_u32 s60, s15
	s_cbranch_scc1 .Lcvb_exit
	s_mul_i32 s0, s14, 0x2500000
	s_add_u32 s18, s6, s0
	s_addc_u32 s19, s7, 0
	s_add_u32 s18, s18, 0x1000000
	s_addc_u32 s19, s19, 0
	v_and_b32_e32 v34, 0xff, v220
	v_lshrrev_b32_e32 v35, 8, v220
	v_and_b32_e32 v64, 31, v220
	v_bfe_u32 v36, v64, 2, 2
	v_lshlrev_b32_e32 v36, 3, v36
	v_lshrrev_b32_e32 v37, 4, v64
	v_lshl_add_u32 v36, v37, 2, v36
	v_and_b32_e32 v37, 3, v64
	v_add_u32_e32 v64, v36, v37
	v_bfe_u32 v36, v34, 5, 2
	v_lshrrev_b32_e32 v39, 7, v34
	v_lshlrev_b32_e32 v37, 6, v36
	v_lshl_add_u32 v37, v39, 5, v37
	v_add_u32_e32 v37, v37, v64
	v_mul_u32_u24_e32 v38, 0xb00, v39
	v_lshl_add_u32 v38, v36, 5, v38
	v_add_u32_e32 v38, v38, v64
	v_and_b32_e32 v39, 0xe0, v34
	v_add_u32_e32 v39, v39, v64
	v_mov_b32_e32 v36, v34
	v_mul_u32_u24_e32 v40, 0x101, v35
	v_add_u32_e32 v40, v40, v34
	v_lshlrev_b32_e32 v40, 2, v40
	v_and_b32_e32 v44, 7, v220
	v_lshrrev_b32_e32 v64, 3, v220
	v_mul_u32_u24_e32 v41, 0x808, v44
	v_add_u32_e32 v41, v41, v64
	v_lshlrev_b32_e32 v41, 2, v41
	v_lshlrev_b32_e32 v42, 11, v64
	v_lshl_add_u32 v42, v44, 4, v42
	v_mul_u32_u24_e32 v43, 0x1600, v64
	v_lshl_add_u32 v43, v44, 4, v43
	v_lshlrev_b32_e32 v44, 5, v44
	s_mov_b32 s13, s60
	s_mov_b32 s34, 0
	s_mov_b32 s0, s13
	s_movk_i32 s1, 576
	s_cmp_lg_u32 s14, 0
	s_cselect_b32 s1, 208, s1
	s_cmp_lt_u32 s0, s1
	s_cbranch_scc1 .Lcvb_j00
	s_sub_u32 s0, s0, s1
	s_cmp_lt_u32 s0, 64
	s_cbranch_scc1 .Lcvb_j10
	s_sub_u32 s0, s0, 64
	s_cmpk_lt_u32 s0, 0x160
	s_cbranch_scc1 .Lcvb_j20
	s_sub_u32 s0, s0, 0x160
	s_mul_i32 s1, s0, 1490
	s_lshr_b32 s1, s1, 16
	s_mul_i32 s100, s1, 44
	s_sub_u32 s0, s0, s100
	v_readlane_b32 s36, v254, 53
	v_readlane_b32 s37, v254, 54
	s_mul_i32 s100, s20, 0xb00000
	s_add_u32 s36, s36, s100
	s_addc_u32 s37, s37, 0
	s_lshl_b32 s100, s0, 18
	s_add_u32 s36, s36, s100
	s_addc_u32 s37, s37, 0
	s_movk_i32 s38, 0x1000
	s_lshl_b32 s39, s1, 8
	s_mov_b32 s101, 0
	s_add_u32 s48, s18, 0x1f00000
	s_addc_u32 s49, s19, 0
	s_mul_i32 s100, s1, 0x160000
	s_add_u32 s48, s48, s100
	s_addc_u32 s49, s49, 0
	s_lshl_b32 s100, s0, 7
	s_add_u32 s48, s48, s100
	s_addc_u32 s49, s49, 0
	s_mov_b32 s50, 0x58000
	s_mov_b32 s51, 0
	s_mov_b32 s16, 1.0
	s_mov_b32 s17, 1
	s_mov_b32 s100, 0
	s_branch .Lcvb_pd0

; DI void convert_layer(const Params& P, LAS unsigned char* lds, int li) {
;     ...
;   for (int t = blockIdx.x; t < tot; t += gridDim.x) {
;     int tt = t;
;     if (tt < cnt[0]) { conv_tile(lds, J[0], tt); continue; } tt -= cnt[0];
;     if (tt < cnt[1]) { conv_tile(lds, J[1], tt); continue; } tt -= cnt[1];
;     if (tt < cnt[2]) { conv_tile(lds, J[2], tt); continue; } tt -= cnt[2];
;     conv_tile(lds, J[3], tt);
;   }
;   __syncthreads();
.Lcvb_exit:
.LBB0_716:
	s_mov_b64 s[72:73], -1
	s_waitcnt vmcnt(0) lgkmcnt(0)
	s_barrier
